# P6 final-norm stores: gains fetched once, 32 stores without waits (hipcc re-fetched gains and waited for store acks 16 times); barrier before LDS reuse
# baseline (speedup 1.0000x reference)
;     __device__ __forceinline__ void fused(f32x4 (&acc)[2][2][4][2], const pg8::Unit& u, int wr, int wc, int fr, int fq, LAS unsigned char* lds, int wid, int lane) const {
;     ...
;         const float qnan = __builtin_nanf("");
; #pragma unroll
;         for (int ai = 0; ai < 2; ++ai)
; #pragma unroll
;             for (int m = 0; m < 4; ++m) { const int r = ai * 128 + wr * 64 + m * 16 + fr; const float rs = bad ? qnan : S[r]; const int row = u.pm * 256 + r;
; #pragma unroll
;                 for (int bj = 0; bj < 2; ++bj) { const int col = colb + bj * 128; const f32x4 g0 = *(const f32x4*)(gfin + col), g1 = *(const f32x4*)(gfin + col + 4);
;                     float* o = out + O_YP + (size_t)row * DM + col; *(f32x4*)o = acc[ai][bj][m][0] * rs * g0; *(f32x4*)(o + 4) = acc[ai][bj][m][1] * rs * g1; } }
.LBB0_1100:
	s_or_b64 exec, exec, s[8:9]
	s_waitcnt lgkmcnt(0)
	s_barrier
	s_waitcnt lgkmcnt(0)
	v_cmp_eq_u32_e32 vcc, 0, v52
	v_lshlrev_b64 v[56:57], 2, v[146:147]
	v_lshl_add_u64 v[54:55], s[12:13], 0, v[56:57]
	global_load_dwordx4 v[66:69], v[54:55], off
	global_load_dwordx4 v[70:73], v[54:55], off offset:16
	global_load_dwordx4 v[82:85], v[54:55], off offset:512
	global_load_dwordx4 v[86:89], v[54:55], off offset:528
	v_add_u32_e32 v52, s37, v1
	v_lshlrev_b32_e32 v1, 2, v1
	ds_read_b32 v50, v1 offset:4096
	v_lshl_add_u32 v52, v52, 12, v56
	s_mov_b32 s6, s14
	s_mov_b32 s7, s15
	s_waitcnt vmcnt(0)
	s_waitcnt lgkmcnt(0)
	ds_read_b32 v51, v1 offset:4160
	s_cbranch_vccnz .Lp6f_good0
	v_mov_b32_e32 v50, 0x7fc00000
.Lp6f_good0:
	v_pk_mul_f32 v[54:55], v[150:151], v[50:51] op_sel_hi:[1,0]
	v_pk_mul_f32 v[56:57], v[148:149], v[50:51] op_sel_hi:[1,0]
	v_pk_mul_f32 v[54:55], v[54:55], v[70:71]
	v_pk_mul_f32 v[56:57], v[56:57], v[72:73]
	global_store_dwordx4 v52, v[54:57], s[6:7] offset:16
	v_pk_mul_f32 v[148:149], v[154:155], v[50:51] op_sel_hi:[1,0]
	v_pk_mul_f32 v[150:151], v[152:153], v[50:51] op_sel_hi:[1,0]
	v_pk_mul_f32 v[148:149], v[148:149], v[66:67]
	v_pk_mul_f32 v[150:151], v[150:151], v[68:69]
	global_store_dwordx4 v52, v[148:151], s[6:7]
	v_pk_mul_f32 v[54:55], v[128:129], v[50:51] op_sel_hi:[1,0]
	v_pk_mul_f32 v[56:57], v[126:127], v[50:51] op_sel_hi:[1,0]
	v_pk_mul_f32 v[54:55], v[54:55], v[82:83]
	v_pk_mul_f32 v[56:57], v[56:57], v[84:85]
	global_store_dwordx4 v52, v[54:57], s[6:7] offset:512
	v_pk_mul_f32 v[148:149], v[124:125], v[50:51] op_sel_hi:[1,0]
	v_pk_mul_f32 v[150:151], v[122:123], v[50:51] op_sel_hi:[1,0]
	v_pk_mul_f32 v[148:149], v[148:149], v[86:87]
	v_pk_mul_f32 v[150:151], v[150:151], v[88:89]
	global_store_dwordx4 v52, v[148:151], s[6:7] offset:528
	s_add_u32 s6, s6, 0x10000
	s_addc_u32 s7, s7, 0
	s_waitcnt lgkmcnt(0)
	v_mov_b32_e32 v50, v51
	ds_read_b32 v51, v1 offset:4224
	s_cbranch_vccnz .Lp6f_good1
	v_mov_b32_e32 v50, 0x7fc00000
.Lp6f_good1:
	v_pk_mul_f32 v[54:55], v[142:143], v[50:51] op_sel_hi:[1,0]
	v_pk_mul_f32 v[56:57], v[112:113], v[50:51] op_sel_hi:[1,0]
	v_pk_mul_f32 v[54:55], v[54:55], v[66:67]
	v_pk_mul_f32 v[56:57], v[56:57], v[68:69]
	global_store_dwordx4 v52, v[54:57], s[6:7]
	v_pk_mul_f32 v[148:149], v[106:107], v[50:51] op_sel_hi:[1,0]
	v_pk_mul_f32 v[150:151], v[108:109], v[50:51] op_sel_hi:[1,0]
	v_pk_mul_f32 v[148:149], v[148:149], v[70:71]
	v_pk_mul_f32 v[150:151], v[150:151], v[72:73]
	global_store_dwordx4 v52, v[148:151], s[6:7] offset:16
	v_pk_mul_f32 v[54:55], v[144:145], v[50:51] op_sel_hi:[1,0]
	v_pk_mul_f32 v[56:57], v[140:141], v[50:51] op_sel_hi:[1,0]
	v_pk_mul_f32 v[54:55], v[54:55], v[82:83]
	v_pk_mul_f32 v[56:57], v[56:57], v[84:85]
	global_store_dwordx4 v52, v[54:57], s[6:7] offset:512
	v_pk_mul_f32 v[148:149], v[138:139], v[50:51] op_sel_hi:[1,0]
	v_pk_mul_f32 v[150:151], v[110:111], v[50:51] op_sel_hi:[1,0]
	v_pk_mul_f32 v[148:149], v[148:149], v[86:87]
	v_pk_mul_f32 v[150:151], v[150:151], v[88:89]
	global_store_dwordx4 v52, v[148:151], s[6:7] offset:528
	s_add_u32 s6, s6, 0x10000
	s_addc_u32 s7, s7, 0
	s_waitcnt lgkmcnt(0)
	v_mov_b32_e32 v50, v51
	ds_read_b32 v51, v1 offset:4288
	s_cbranch_vccnz .Lp6f_good2
	v_mov_b32_e32 v50, 0x7fc00000
.Lp6f_good2:
	v_pk_mul_f32 v[54:55], v[134:135], v[50:51] op_sel_hi:[1,0]
	v_pk_mul_f32 v[56:57], v[96:97], v[50:51] op_sel_hi:[1,0]
	v_pk_mul_f32 v[54:55], v[54:55], v[66:67]
	v_pk_mul_f32 v[56:57], v[56:57], v[68:69]
	global_store_dwordx4 v52, v[54:57], s[6:7]
	v_pk_mul_f32 v[148:149], v[90:91], v[50:51] op_sel_hi:[1,0]
	v_pk_mul_f32 v[150:151], v[92:93], v[50:51] op_sel_hi:[1,0]
	v_pk_mul_f32 v[148:149], v[148:149], v[70:71]
	v_pk_mul_f32 v[150:151], v[150:151], v[72:73]
	global_store_dwordx4 v52, v[148:151], s[6:7] offset:16
	v_pk_mul_f32 v[54:55], v[136:137], v[50:51] op_sel_hi:[1,0]
	v_pk_mul_f32 v[56:57], v[132:133], v[50:51] op_sel_hi:[1,0]
	v_pk_mul_f32 v[54:55], v[54:55], v[82:83]
	v_pk_mul_f32 v[56:57], v[56:57], v[84:85]
	global_store_dwordx4 v52, v[54:57], s[6:7] offset:512
	v_pk_mul_f32 v[148:149], v[130:131], v[50:51] op_sel_hi:[1,0]
	v_pk_mul_f32 v[150:151], v[94:95], v[50:51] op_sel_hi:[1,0]
	v_pk_mul_f32 v[148:149], v[148:149], v[86:87]
	v_pk_mul_f32 v[150:151], v[150:151], v[88:89]
	global_store_dwordx4 v52, v[148:151], s[6:7] offset:528
	s_add_u32 s6, s6, 0x10000
	s_addc_u32 s7, s7, 0
	s_waitcnt lgkmcnt(0)
	v_mov_b32_e32 v50, v51
	ds_read_b32 v51, v1 offset:4608
	s_cbranch_vccnz .Lp6f_good3
	v_mov_b32_e32 v50, 0x7fc00000
.Lp6f_good3:
	v_pk_mul_f32 v[54:55], v[118:119], v[50:51] op_sel_hi:[1,0]
	v_pk_mul_f32 v[56:57], v[80:81], v[50:51] op_sel_hi:[1,0]
	v_pk_mul_f32 v[54:55], v[54:55], v[66:67]
	v_pk_mul_f32 v[56:57], v[56:57], v[68:69]
	global_store_dwordx4 v52, v[54:57], s[6:7]
	v_pk_mul_f32 v[148:149], v[74:75], v[50:51] op_sel_hi:[1,0]
	v_pk_mul_f32 v[150:151], v[76:77], v[50:51] op_sel_hi:[1,0]
	v_pk_mul_f32 v[148:149], v[148:149], v[70:71]
	v_pk_mul_f32 v[150:151], v[150:151], v[72:73]
	global_store_dwordx4 v52, v[148:151], s[6:7] offset:16
	v_pk_mul_f32 v[54:55], v[120:121], v[50:51] op_sel_hi:[1,0]
	v_pk_mul_f32 v[56:57], v[116:117], v[50:51] op_sel_hi:[1,0]
	v_pk_mul_f32 v[54:55], v[54:55], v[82:83]
	v_pk_mul_f32 v[56:57], v[56:57], v[84:85]
	global_store_dwordx4 v52, v[54:57], s[6:7] offset:512
	v_pk_mul_f32 v[148:149], v[114:115], v[50:51] op_sel_hi:[1,0]
	v_pk_mul_f32 v[150:151], v[78:79], v[50:51] op_sel_hi:[1,0]
	v_pk_mul_f32 v[148:149], v[148:149], v[86:87]
	v_pk_mul_f32 v[150:151], v[150:151], v[88:89]
	global_store_dwordx4 v52, v[148:151], s[6:7] offset:528
	s_add_u32 s6, s6, 0x50000
	s_addc_u32 s7, s7, 0
	s_waitcnt lgkmcnt(0)
	v_mov_b32_e32 v50, v51
	ds_read_b32 v51, v1 offset:4672
	s_cbranch_vccnz .Lp6f_good4
	v_mov_b32_e32 v50, 0x7fc00000
;     __device__ __forceinline__ void fused(f32x4 (&acc)[2][2][4][2], const pg8::Unit& u, int wr, int wc, int fr, int fq, LAS unsigned char* lds, int wid, int lane) const {
;     ...
;         const float qnan = __builtin_nanf("");
; #pragma unroll
;         for (int ai = 0; ai < 2; ++ai)
; #pragma unroll
;             for (int m = 0; m < 4; ++m) { const int r = ai * 128 + wr * 64 + m * 16 + fr; const float rs = bad ? qnan : S[r]; const int row = u.pm * 256 + r;
; #pragma unroll
;                 for (int bj = 0; bj < 2; ++bj) { const int col = colb + bj * 128; const f32x4 g0 = *(const f32x4*)(gfin + col), g1 = *(const f32x4*)(gfin + col + 4);
;                     float* o = out + O_YP + (size_t)row * DM + col; *(f32x4*)o = acc[ai][bj][m][0] * rs * g0; *(f32x4*)(o + 4) = acc[ai][bj][m][1] * rs * g1; } }
.Lp6f_good4:
	v_pk_mul_f32 v[54:55], v[102:103], v[50:51] op_sel_hi:[1,0]
	v_pk_mul_f32 v[56:57], v[64:65], v[50:51] op_sel_hi:[1,0]
	v_pk_mul_f32 v[54:55], v[54:55], v[66:67]
	v_pk_mul_f32 v[56:57], v[56:57], v[68:69]
	global_store_dwordx4 v52, v[54:57], s[6:7]
	v_pk_mul_f32 v[148:149], v[58:59], v[50:51] op_sel_hi:[1,0]
	v_pk_mul_f32 v[150:151], v[60:61], v[50:51] op_sel_hi:[1,0]
	v_pk_mul_f32 v[148:149], v[148:149], v[70:71]
	v_pk_mul_f32 v[150:151], v[150:151], v[72:73]
	global_store_dwordx4 v52, v[148:151], s[6:7] offset:16
	v_pk_mul_f32 v[54:55], v[104:105], v[50:51] op_sel_hi:[1,0]
	v_pk_mul_f32 v[56:57], v[100:101], v[50:51] op_sel_hi:[1,0]
	v_pk_mul_f32 v[54:55], v[54:55], v[82:83]
	v_pk_mul_f32 v[56:57], v[56:57], v[84:85]
	global_store_dwordx4 v52, v[54:57], s[6:7] offset:512
	v_pk_mul_f32 v[148:149], v[98:99], v[50:51] op_sel_hi:[1,0]
	v_pk_mul_f32 v[150:151], v[62:63], v[50:51] op_sel_hi:[1,0]
	v_pk_mul_f32 v[148:149], v[148:149], v[86:87]
	v_pk_mul_f32 v[150:151], v[150:151], v[88:89]
	global_store_dwordx4 v52, v[148:151], s[6:7] offset:528
	s_add_u32 s6, s6, 0x10000
	s_addc_u32 s7, s7, 0
	s_waitcnt lgkmcnt(0)
	v_mov_b32_e32 v50, v51
	ds_read_b32 v51, v1 offset:4736
	s_cbranch_vccnz .Lp6f_good5
	v_mov_b32_e32 v50, 0x7fc00000
.Lp6f_good5:
	v_pk_mul_f32 v[54:55], v[46:47], v[50:51] op_sel_hi:[1,0]
	v_pk_mul_f32 v[56:57], v[48:49], v[50:51] op_sel_hi:[1,0]
	v_pk_mul_f32 v[54:55], v[54:55], v[66:67]
	v_pk_mul_f32 v[56:57], v[56:57], v[68:69]
	global_store_dwordx4 v52, v[54:57], s[6:7]
	v_pk_mul_f32 v[148:149], v[42:43], v[50:51] op_sel_hi:[1,0]
	v_pk_mul_f32 v[150:151], v[44:45], v[50:51] op_sel_hi:[1,0]
	v_pk_mul_f32 v[148:149], v[148:149], v[70:71]
	v_pk_mul_f32 v[150:151], v[150:151], v[72:73]
	global_store_dwordx4 v52, v[148:151], s[6:7] offset:16
	v_pk_mul_f32 v[54:55], v[38:39], v[50:51] op_sel_hi:[1,0]
	v_pk_mul_f32 v[56:57], v[40:41], v[50:51] op_sel_hi:[1,0]
	v_pk_mul_f32 v[54:55], v[54:55], v[82:83]
	v_pk_mul_f32 v[56:57], v[56:57], v[84:85]
	global_store_dwordx4 v52, v[54:57], s[6:7] offset:512
	v_pk_mul_f32 v[148:149], v[34:35], v[50:51] op_sel_hi:[1,0]
	v_pk_mul_f32 v[150:151], v[36:37], v[50:51] op_sel_hi:[1,0]
	v_pk_mul_f32 v[148:149], v[148:149], v[86:87]
	v_pk_mul_f32 v[150:151], v[150:151], v[88:89]
	global_store_dwordx4 v52, v[148:151], s[6:7] offset:528
	s_add_u32 s6, s6, 0x10000
	s_addc_u32 s7, s7, 0
	s_waitcnt lgkmcnt(0)
	v_mov_b32_e32 v50, v51
	ds_read_b32 v51, v1 offset:4800
	s_cbranch_vccnz .Lp6f_good6
	v_mov_b32_e32 v50, 0x7fc00000
.Lp6f_good6:
	v_pk_mul_f32 v[54:55], v[30:31], v[50:51] op_sel_hi:[1,0]
	v_pk_mul_f32 v[56:57], v[32:33], v[50:51] op_sel_hi:[1,0]
	v_pk_mul_f32 v[54:55], v[54:55], v[66:67]
	v_pk_mul_f32 v[56:57], v[56:57], v[68:69]
	global_store_dwordx4 v52, v[54:57], s[6:7]
	v_pk_mul_f32 v[148:149], v[26:27], v[50:51] op_sel_hi:[1,0]
	v_pk_mul_f32 v[150:151], v[28:29], v[50:51] op_sel_hi:[1,0]
	v_pk_mul_f32 v[148:149], v[148:149], v[70:71]
	v_pk_mul_f32 v[150:151], v[150:151], v[72:73]
	global_store_dwordx4 v52, v[148:151], s[6:7] offset:16
	v_pk_mul_f32 v[54:55], v[22:23], v[50:51] op_sel_hi:[1,0]
	v_pk_mul_f32 v[56:57], v[24:25], v[50:51] op_sel_hi:[1,0]
	v_pk_mul_f32 v[54:55], v[54:55], v[82:83]
	v_pk_mul_f32 v[56:57], v[56:57], v[84:85]
	global_store_dwordx4 v52, v[54:57], s[6:7] offset:512
	v_pk_mul_f32 v[148:149], v[18:19], v[50:51] op_sel_hi:[1,0]
	v_pk_mul_f32 v[150:151], v[20:21], v[50:51] op_sel_hi:[1,0]
	v_pk_mul_f32 v[148:149], v[148:149], v[86:87]
	v_pk_mul_f32 v[150:151], v[150:151], v[88:89]
	global_store_dwordx4 v52, v[148:151], s[6:7] offset:528
	s_add_u32 s6, s6, 0x10000
	s_addc_u32 s7, s7, 0
	s_waitcnt lgkmcnt(0)
	s_barrier
	v_mov_b32_e32 v50, v51
	s_cbranch_vccnz .Lp6f_good7
	v_mov_b32_e32 v50, 0x7fc00000
; #define LAS __attribute__((address_space(3)))
;     __device__ __forceinline__ void fused(f32x4 (&acc)[2][2][4][2], const pg8::Unit& u, int wr, int wc, int fr, int fq, LAS unsigned char* lds, int wid, int lane) const {
;     ...
;             for (int m = 0; m < 4; ++m) { const int r = ai * 128 + wr * 64 + m * 16 + fr; const float rs = bad ? qnan : S[r]; const int row = u.pm * 256 + r;
; #pragma unroll
;                 for (int bj = 0; bj < 2; ++bj) { const int col = colb + bj * 128; const f32x4 g0 = *(const f32x4*)(gfin + col), g1 = *(const f32x4*)(gfin + col + 4);
;                     float* o = out + O_YP + (size_t)row * DM + col; *(f32x4*)o = acc[ai][bj][m][0] * rs * g0; *(f32x4*)(o + 4) = acc[ai][bj][m][1] * rs * g1; } }
; template <int NSEG, int KST, int CK, int NBUF, class Fin>
; __device__ __forceinline__ void tail_gemm(LAS unsigned char* lds, const bf16_t* A0, const bf16_t* A1, const bf16_t* A2, const bf16_t* Bt, const bf16_t* G, const Fin& fin, int G_, int bx) {
;     constexpr int Kseg = KST * 256;
;     constexpr bool GATED = NSEG > 1;
;     constexpr int CPS = (KST + CK - 1) / CK, CPT = NSEG * CPS, NCH = 2 * CPT;
;     const int tid = threadIdx.x, wid = __builtin_amdgcn_readfirstlane(tid >> 6), lane = tid & 63, fr = lane & 15, fq = lane >> 4;
;     const int kbase = wid * (KST * 32);
;     LAS float* part = (LAS float*)lds;
;     bf16x8 af[NBUF][CK][2], wf[NBUF][CK][2]; u32x2 gg[NBUF][2][2];
.Lp6f_good7:
	v_pk_mul_f32 v[54:55], v[14:15], v[50:51] op_sel_hi:[1,0]
	v_pk_mul_f32 v[56:57], v[16:17], v[50:51] op_sel_hi:[1,0]
	v_pk_mul_f32 v[54:55], v[54:55], v[66:67]
	v_pk_mul_f32 v[56:57], v[56:57], v[68:69]
	global_store_dwordx4 v52, v[54:57], s[6:7]
	v_pk_mul_f32 v[148:149], v[10:11], v[50:51] op_sel_hi:[1,0]
	v_pk_mul_f32 v[150:151], v[12:13], v[50:51] op_sel_hi:[1,0]
	v_pk_mul_f32 v[148:149], v[148:149], v[70:71]
	v_pk_mul_f32 v[150:151], v[150:151], v[72:73]
	global_store_dwordx4 v52, v[148:151], s[6:7] offset:16
	v_pk_mul_f32 v[54:55], v[6:7], v[50:51] op_sel_hi:[1,0]
	v_pk_mul_f32 v[56:57], v[8:9], v[50:51] op_sel_hi:[1,0]
	v_pk_mul_f32 v[54:55], v[54:55], v[82:83]
	v_pk_mul_f32 v[56:57], v[56:57], v[84:85]
	global_store_dwordx4 v52, v[54:57], s[6:7] offset:512
	v_pk_mul_f32 v[148:149], v[2:3], v[50:51] op_sel_hi:[1,0]
	v_pk_mul_f32 v[150:151], v[4:5], v[50:51] op_sel_hi:[1,0]
	v_pk_mul_f32 v[148:149], v[148:149], v[86:87]
	v_pk_mul_f32 v[150:151], v[150:151], v[88:89]
	global_store_dwordx4 v52, v[148:151], s[6:7] offset:528
	s_branch .Lp6f_end
	s_nop 0
	s_nop 0
	s_nop 0
	s_nop 0
	s_nop 0
	s_nop 0
	s_nop 0
	s_nop 0
	s_nop 0
	s_nop 0
	s_nop 0
	s_nop 0
	s_nop 0
	s_nop 0
	s_nop 0
	s_nop 0
	s_nop 0
	s_nop 0
	s_nop 0
	s_nop 0
	s_nop 0
	s_nop 0
	s_nop 0
	s_nop 0
	s_nop 0
	s_nop 0
	s_nop 0
	s_nop 0
	s_nop 0
	s_nop 0
	s_nop 0
	s_nop 0
	s_nop 0
	s_nop 0
	s_nop 0
	s_nop 0
	s_nop 0
	s_nop 0
	s_nop 0
	s_nop 0
	s_nop 0
	s_nop 0
	s_nop 0
	s_nop 0
	s_nop 0
	s_nop 0
	s_nop 0
	s_nop 0
	s_nop 0
	s_nop 0
	s_nop 0
	s_nop 0
	s_nop 0
	s_nop 0
	s_nop 0
	s_nop 0
	s_nop 0
	s_nop 0
	s_nop 0
	s_nop 0
	s_nop 0
	s_nop 0
	s_nop 0
	s_nop 0
	s_nop 0
	s_nop 0
	s_nop 0
	s_nop 0
	s_nop 0
	s_nop 0
	s_nop 0
	s_nop 0
	s_nop 0
	s_nop 0
	s_nop 0
	s_nop 0
	s_nop 0
	s_nop 0
	s_nop 0
	s_nop 0
	s_nop 0
	s_nop 0
	s_nop 0
	s_nop 0
	s_nop 0
	s_nop 0
	s_nop 0
	s_nop 0
	s_nop 0
	s_nop 0
	s_nop 0
	s_nop 0
	s_nop 0
	s_nop 0
	s_nop 0
	s_nop 0
	s_nop 0
	s_nop 0
	s_nop 0
	s_nop 0
	s_nop 0
	s_nop 0
	s_nop 0
	s_nop 0
	s_nop 0
	s_nop 0
	s_nop 0
	s_nop 0
	s_nop 0
	s_nop 0
	s_nop 0
	s_nop 0
	s_nop 0
	s_nop 0
	s_nop 0
	s_nop 0
	s_nop 0
	s_nop 0
	s_nop 0
	s_nop 0
	s_nop 0
	s_nop 0
	s_nop 0
	s_nop 0
	s_nop 0
	s_nop 0
	s_nop 0
	s_nop 0
	s_nop 0
	s_nop 0
	s_nop 0
	s_nop 0
	s_nop 0
	s_nop 0
	s_nop 0
	s_nop 0
	s_nop 0
	s_nop 0
	s_nop 0
	s_nop 0
	s_nop 0
	s_nop 0
	s_nop 0
	s_nop 0
	s_nop 0
	s_nop 0
	s_nop 0
	s_nop 0
	s_nop 0
	s_nop 0
	s_nop 0
	s_nop 0
.Lp6f_end:
.LBB0_1117:
	s_andn2_b64 vcc, exec, s[20:21]
	v_readfirstlane_b32 s6, v0
	s_cbranch_vccnz .LBB0_1136
	s_add_u32 s8, s18, 0xc000000
	s_addc_u32 s9, s19, 0
	s_lshr_b32 s12, s6, 6
	s_mul_i32 s6, s12, 0x160
	s_mov_b32 s7, 0
	s_lshl_b64 s[6:7], s[6:7], 1
	s_add_u32 s10, s29, s6
	s_addc_u32 s11, s31, s7
	s_add_u32 s6, s3, s6
	v_and_b32_e32 v192, 48, v0
	v_mov_b32_e32 v193, 0
	s_addc_u32 s7, s28, s7
	v_lshlrev_b32_e32 v1, 7, v199
	s_movk_i32 s3, 0x100
	v_and_b32_e32 v201, 28, v239
	v_lshl_add_u64 v[196:197], s[6:7], 0, v[192:193]
	v_lshl_or_b32 v1, s12, 12, v1
	v_cmp_gt_u32_e64 s[6:7], s3, v0
	v_lshlrev_b32_e32 v0, 2, v201
	v_or_b32_e32 v200, 0x4000, v199
	v_lshl_add_u64 v[194:195], s[10:11], 0, v[192:193]
	v_lshl_or_b32 v202, v198, 7, v0
	s_lshl_b32 s3, s76, 6
	s_lshl_b32 s12, s78, 6
	s_lshl_b32 s13, s76, 1
	s_lshl_b32 s14, s78, 1
	s_movk_i32 s15, 0x1600
	v_add_u32_e32 v203, v1, v192
	s_branch .LBB0_1120
